# GU epilogue: cache the 8 row scales across tiles with the same row block (skip rsp loads, vmcnt(0), reduce)
# speedup vs baseline: 1.0725x; 1.0152x over previous
.LBB0_1432:
	s_and_b64 vcc, exec, s[2:3]
	s_cbranch_vccz .LBB0_1671
	s_mov_b32 s101, -1
	v_readlane_b32 s0, v254, 12
	v_readlane_b32 s1, v254, 13
	s_add_u32 s24, s0, 0x100000
	s_addc_u32 s25, s1, 0
	s_andn2_b64 vcc, exec, s[74:75]
	v_readfirstlane_b32 s0, v222
	s_cbranch_vccnz .LBB0_1453
	s_waitcnt vmcnt(0)
	v_lshlrev_b32_e32 v0, 4, v222
	v_add_u32_e32 v2, 0x2000, v0
	s_waitcnt lgkmcnt(0)
	v_ashrrev_i32_e32 v3, 31, v2
	v_lshrrev_b32_e32 v3, 22, v3
	v_add_u32_e32 v3, v2, v3
	v_ashrrev_i32_e32 v10, 10, v3
	v_mul_i32_i24_e32 v3, 0x400, v10
	v_sub_u32_e32 v2, v2, v3
	v_lshrrev_b32_e32 v3, 4, v2
	v_bitop3_b32 v2, v3, v2, 32 bitop3:0x6c
	v_ashrrev_i32_e32 v3, 31, v2
	v_lshrrev_b32_e32 v3, 26, v3
	v_add_u32_e32 v3, v2, v3
	v_lshlrev_b32_e32 v4, 3, v10
	v_ashrrev_i32_e32 v11, 6, v3
	v_and_b32_e32 v4, -16, v4
	v_readlane_b32 s1, v254, 19
	v_readlane_b32 s2, v254, 24
	v_add_u32_e32 v4, v11, v4
	s_or_b32 s1, s2, s1
	v_and_b32_e32 v5, 3, v11
	s_mov_b32 s2, 0x1fffe0
	v_lshrrev_b32_e32 v6, 2, v4
	v_lshlrev_b32_e32 v7, 1, v4
	v_and_b32_e32 v3, 0xc0, v3
	v_and_or_b32 v5, v4, s2, v5
	v_and_b32_e32 v6, 4, v6
	v_and_b32_e32 v7, 24, v7
	v_sub_u32_e32 v2, v2, v3
	v_or3_b32 v5, v5, v6, v7
	v_lshlrev_b32_e32 v6, 5, v10
	v_ashrrev_i16_sdwa v2, v241, sext(v2) dst_sel:DWORD dst_unused:UNUSED_PAD src0_sel:DWORD src1_sel:BYTE_0
	v_and_b32_e32 v6, 32, v6
	v_bfe_i32 v12, v2, 0, 16
	v_add_lshl_u32 v2, v6, v12, 1
	v_lshl_add_u32 v154, v5, 11, v2
	v_lshl_add_u32 v156, v4, 11, v2
	v_bfe_i32 v2, v222, 27, 1
	v_lshrrev_b32_e32 v2, 22, v2
	v_add_u32_e32 v2, v0, v2
	v_and_b32_e32 v2, 0xfffffc00, v2
	v_sub_u32_e32 v0, v0, v2
	v_lshrrev_b32_e32 v2, 4, v0
	v_ashrrev_i32_e32 v3, 31, v222
	v_bitop3_b32 v0, v2, v0, 32 bitop3:0x6c
	v_lshrrev_b32_e32 v3, 26, v3
	v_ashrrev_i32_e32 v2, 31, v0
	v_add_u32_e32 v3, v222, v3
	v_lshrrev_b32_e32 v2, 26, v2
	v_ashrrev_i32_e32 v14, 6, v3
	v_add_u32_e32 v2, v0, v2
	v_lshlrev_b32_e32 v3, 3, v14
	v_ashrrev_i32_e32 v13, 6, v2
	v_and_b32_e32 v3, -16, v3
	s_mul_i32 s1, s1, 0xb00000
	v_add_u32_e32 v3, v13, v3
	s_add_u32 s20, s24, s1
	v_and_b32_e32 v4, 3, v13
	v_lshrrev_b32_e32 v5, 2, v3
	v_lshlrev_b32_e32 v6, 1, v3
	v_and_b32_e32 v2, 0xc0, v2
	s_addc_u32 s21, s25, 0
	s_ashr_i32 s6, s0, 6
	v_and_or_b32 v4, v3, s2, v4
	v_and_b32_e32 v5, 4, v5
	v_and_b32_e32 v6, 24, v6
	v_sub_u32_e32 v0, v0, v2
	s_ashr_i32 s1, s0, 8
	s_lshl_b32 s22, s6, 10
	v_or3_b32 v4, v4, v5, v6
	v_lshlrev_b32_e32 v5, 5, v14
	v_ashrrev_i16_sdwa v0, v241, sext(v0) dst_sel:DWORD dst_unused:UNUSED_PAD src0_sel:DWORD src1_sel:BYTE_0
	v_and_b32_e32 v5, 32, v5
	v_bfe_i32 v15, v0, 0, 16
	s_add_u32 s16, s20, s82
	v_add_lshl_u32 v2, v5, v15, 1
	s_addc_u32 s17, s21, s83
	s_add_i32 s23, s22, 0
	v_lshl_add_u32 v0, v4, 11, v2
	s_add_i32 m0, s23, 0x10000
	v_lshl_add_u32 v158, v3, 11, v2
	global_load_lds_dwordx4 v0, s[16:17]
	s_add_i32 m0, s23, 0x12000
	s_add_u32 s2, s16, 0x40000
	global_load_lds_dwordx4 v154, s[16:17]
	s_addc_u32 s3, s17, 0
	s_add_i32 m0, s23, 0x14000
	v_mov_b32_e32 v155, v1
	global_load_lds_dwordx4 v0, s[2:3]
	s_add_i32 m0, s23, 0x16000
	v_mov_b32_e32 v159, v1
	global_load_lds_dwordx4 v154, s[2:3]
	v_readlane_b32 s2, v254, 28
	v_readlane_b32 s3, v254, 29
	s_add_u32 s4, s2, s80
	s_addc_u32 s5, s3, s81
	s_add_i32 s26, s23, 0x2000
	s_mov_b32 m0, s23
	s_add_u32 s2, s4, 0x40000
	global_load_lds_dwordx4 v158, s[4:5]
	s_mov_b32 m0, s26
	s_addc_u32 s3, s5, 0
	s_add_i32 s27, s23, 0x4000
	global_load_lds_dwordx4 v156, s[4:5]
	s_mov_b32 m0, s27
	s_add_i32 s28, s23, 0x6000
	global_load_lds_dwordx4 v158, s[2:3]
	s_mov_b32 m0, s28
	v_mov_b32_e32 v157, v1
	global_load_lds_dwordx4 v156, s[2:3]
	s_cmp_eq_u32 s1, 1
	v_lshl_add_u64 v[8:9], s[16:17], 0, v[0:1]
	v_lshl_add_u64 v[6:7], s[16:17], 0, v[154:155]
	v_lshl_add_u64 v[2:3], s[4:5], 0, v[158:159]
	s_cselect_b64 s[2:3], -1, 0
	s_cmp_lg_u32 s1, 1
	v_lshl_add_u64 v[4:5], s[4:5], 0, v[156:157]
	s_cbranch_scc1 .LBB0_1436
	s_barrier

.LBB0_1449:
	s_cmp_eq_u32 s101, s36
	s_cbranch_scc1 .Lgu_rs_cached
	v_lshl_add_u32 v188, s36, 8, v193
	v_ashrrev_i32_e32 v189, 31, v188
	v_lshlrev_b64 v[130:131], 6, v[188:189]
	v_or_b32_e32 v186, 16, v188
	v_lshl_add_u64 v[130:131], v[160:161], 0, v[130:131]
	v_ashrrev_i32_e32 v187, 31, v186
	global_load_dwordx4 v[200:203], v[130:131], off
	v_lshlrev_b64 v[130:131], 6, v[186:187]
	v_lshl_add_u64 v[130:131], v[160:161], 0, v[130:131]
	global_load_dwordx4 v[204:207], v[130:131], off
	v_or_b32_e32 v184, 32, v188
	v_ashrrev_i32_e32 v185, 31, v184
	v_lshlrev_b64 v[130:131], 6, v[184:185]
	v_or_b32_e32 v182, 48, v188
	v_lshl_add_u64 v[130:131], v[160:161], 0, v[130:131]
	v_ashrrev_i32_e32 v183, 31, v182
	global_load_dwordx4 v[150:153], v[130:131], off
	v_lshlrev_b64 v[130:131], 6, v[182:183]
	v_lshl_add_u64 v[130:131], v[160:161], 0, v[130:131]
	global_load_dwordx4 v[146:149], v[130:131], off
	v_add_u32_e32 v180, 0x80, v188
	v_ashrrev_i32_e32 v181, 31, v180
	v_lshlrev_b64 v[130:131], 6, v[180:181]
	v_add_u32_e32 v178, 0x90, v188
	v_lshl_add_u64 v[130:131], v[160:161], 0, v[130:131]
	v_ashrrev_i32_e32 v179, 31, v178
	global_load_dwordx4 v[142:145], v[130:131], off
	v_lshlrev_b64 v[130:131], 6, v[178:179]
	v_lshl_add_u64 v[130:131], v[160:161], 0, v[130:131]
	global_load_dwordx4 v[138:141], v[130:131], off
	v_add_u32_e32 v176, 0xa0, v188
	v_ashrrev_i32_e32 v177, 31, v176
	v_lshlrev_b64 v[130:131], 6, v[176:177]
	v_add_u32_e32 v174, 0xb0, v188
	v_lshl_add_u64 v[130:131], v[160:161], 0, v[130:131]
	v_ashrrev_i32_e32 v175, 31, v174
	global_load_dwordx4 v[134:137], v[130:131], off
	v_lshlrev_b64 v[130:131], 6, v[174:175]
	v_lshl_add_u64 v[130:131], v[160:161], 0, v[130:131]
	global_load_dwordx4 v[130:133], v[130:131], off
	v_and_b32_e32 v163, 64, v211
	v_xor_b32_e32 v162, 16, v211
	v_add_u32_e32 v163, 64, v163
	v_cmp_lt_i32_e32 vcc, v162, v163
	s_mov_b32 s4, 0x358637bd
	s_mov_b32 s16, 0x3a800000
	v_cndmask_b32_e32 v162, v211, v162, vcc
	v_lshlrev_b32_e32 v177, 2, v162
	v_xor_b32_e32 v162, 32, v211
	v_cmp_lt_i32_e32 vcc, v162, v163
	v_lshl_or_b32 v190, s35, 7, v198
	v_ashrrev_i32_e32 v191, 31, v190
	v_cndmask_b32_e32 v162, v211, v162, vcc
	v_lshlrev_b32_e32 v175, 2, v162
	s_movk_i32 s9, 0x1600
	s_waitcnt vmcnt(0)
	v_mov_b32_e32 v162, v201
	v_mov_b32_e32 v163, v202
	v_mov_b32_e32 v201, v203
	v_mov_b32_e32 v196, v205
	v_mov_b32_e32 v197, v206
	v_mov_b32_e32 v205, v207
	v_pk_add_f32 v[162:163], v[162:163], v[200:201]
	v_pk_add_f32 v[196:197], v[196:197], v[204:205]
	v_mov_b32_e32 v201, v162
	v_mov_b32_e32 v200, v196
	v_mov_b32_e32 v162, v197
	v_pk_add_f32 v[162:163], v[200:201], v[162:163]
	ds_bpermute_b32 v197, v177, v163
	ds_bpermute_b32 v196, v177, v162
	s_waitcnt lgkmcnt(0)
	v_pk_add_f32 v[162:163], v[162:163], v[196:197]
	ds_bpermute_b32 v197, v175, v163
	ds_bpermute_b32 v196, v175, v162
	s_waitcnt lgkmcnt(0)
	v_pk_add_f32 v[162:163], v[162:163], v[196:197]
	v_mov_b64_e32 v[196:197], s[4:5]
	v_pk_fma_f32 v[162:163], v[162:163], s[16:17], v[196:197] op_sel_hi:[1,0,0]
	s_nop 0
	v_mul_f32_e32 v164, 0x4b800000, v163
	v_cmp_gt_f32_e64 s[4:5], s91, v163
	v_cmp_gt_f32_e32 vcc, s91, v162
	s_nop 0
	v_cndmask_b32_e64 v163, v163, v164, s[4:5]
	v_rsq_f32_e32 v163, v163
	s_nop 0
	v_mul_f32_e32 v164, 0x45800000, v163
	v_cndmask_b32_e64 v194, v163, v164, s[4:5]
	v_mul_f32_e32 v163, 0x4b800000, v162
	v_cndmask_b32_e32 v162, v162, v163, vcc
	v_rsq_f32_e32 v162, v162
	s_nop 0
	s_nop 0
	s_nop 0
	v_mul_f32_e32 v163, 0x45800000, v162
	v_cndmask_b32_e32 v192, v162, v163, vcc
	v_mov_b32_e32 v162, v151
	v_mov_b32_e32 v163, v152
	v_mov_b32_e32 v151, v153
	v_mov_b32_e32 v152, v147
	v_mov_b32_e32 v153, v148
	v_mov_b32_e32 v147, v149
	v_pk_add_f32 v[150:151], v[162:163], v[150:151]
	v_pk_add_f32 v[146:147], v[152:153], v[146:147]
	v_mov_b32_e32 v149, v150
	v_mov_b32_e32 v148, v146
	v_mov_b32_e32 v150, v147
	v_pk_add_f32 v[146:147], v[148:149], v[150:151]
	ds_bpermute_b32 v149, v177, v147
	ds_bpermute_b32 v148, v177, v146
	v_mov_b32_e32 v150, v143
	v_mov_b32_e32 v151, v144
	v_mov_b32_e32 v143, v145
	v_mov_b32_e32 v144, v139
	v_mov_b32_e32 v145, v140
	v_mov_b32_e32 v139, v141
	v_pk_add_f32 v[142:143], v[150:151], v[142:143]
	v_pk_add_f32 v[138:139], v[144:145], v[138:139]
	s_waitcnt lgkmcnt(0)
	v_pk_add_f32 v[146:147], v[146:147], v[148:149]
	v_mov_b32_e32 v140, v138
	v_mov_b32_e32 v141, v142
	v_mov_b32_e32 v142, v139
	ds_bpermute_b32 v149, v175, v147
	ds_bpermute_b32 v148, v175, v146
	v_pk_add_f32 v[138:139], v[140:141], v[142:143]
	ds_bpermute_b32 v141, v177, v139
	ds_bpermute_b32 v140, v177, v138
	v_mov_b32_e32 v142, v135
	v_mov_b32_e32 v143, v136
	v_mov_b32_e32 v135, v137
	v_mov_b32_e32 v136, v131
	v_mov_b32_e32 v137, v132
	v_mov_b32_e32 v131, v133
	s_waitcnt lgkmcnt(2)
	v_pk_add_f32 v[146:147], v[146:147], v[148:149]
	v_pk_add_f32 v[134:135], v[142:143], v[134:135]
	v_pk_add_f32 v[130:131], v[136:137], v[130:131]
	v_pk_fma_f32 v[146:147], v[146:147], s[16:17], v[196:197] op_sel_hi:[1,0,0]
	s_waitcnt lgkmcnt(0)
	v_pk_add_f32 v[138:139], v[138:139], v[140:141]
	v_mov_b32_e32 v132, v130
	v_mov_b32_e32 v133, v134
	v_mov_b32_e32 v134, v131
	v_mul_f32_e32 v148, 0x4b800000, v147
	v_cmp_gt_f32_e64 s[4:5], s91, v147
	ds_bpermute_b32 v141, v175, v139
	ds_bpermute_b32 v140, v175, v138
	v_pk_add_f32 v[130:131], v[132:133], v[134:135]
	v_cndmask_b32_e64 v147, v147, v148, s[4:5]
	ds_bpermute_b32 v133, v177, v131
	ds_bpermute_b32 v132, v177, v130
	v_rsq_f32_e32 v147, v147
	s_waitcnt lgkmcnt(2)
	v_pk_add_f32 v[138:139], v[138:139], v[140:141]
	v_cmp_gt_f32_e32 vcc, s91, v146
	v_pk_fma_f32 v[138:139], v[138:139], s[16:17], v[196:197] op_sel_hi:[1,0,0]
	v_mul_f32_e32 v148, 0x45800000, v147
	s_waitcnt lgkmcnt(0)
	v_pk_add_f32 v[130:131], v[130:131], v[132:133]
	v_cndmask_b32_e64 v148, v147, v148, s[4:5]
	v_mul_f32_e32 v147, 0x4b800000, v146
	v_mul_f32_e32 v140, 0x4b800000, v139
	v_cmp_gt_f32_e64 s[4:5], s91, v139
	ds_bpermute_b32 v133, v175, v131
	ds_bpermute_b32 v132, v175, v130
	v_cndmask_b32_e32 v146, v146, v147, vcc
	v_cndmask_b32_e64 v139, v139, v140, s[4:5]
	v_rsq_f32_e32 v146, v146
	v_rsq_f32_e32 v139, v139
	s_waitcnt lgkmcnt(0)
	v_pk_add_f32 v[130:131], v[130:131], v[132:133]
	s_nop 0
	v_mul_f32_e32 v147, 0x45800000, v146
	v_mul_f32_e32 v140, 0x45800000, v139
	v_pk_fma_f32 v[130:131], v[130:131], s[16:17], v[196:197] op_sel_hi:[1,0,0]
	v_cndmask_b32_e32 v146, v146, v147, vcc
	v_cmp_gt_f32_e32 vcc, s91, v138
	v_cndmask_b32_e64 v140, v139, v140, s[4:5]
	v_mul_f32_e32 v139, 0x4b800000, v138
	v_mul_f32_e32 v132, 0x4b800000, v131
	v_cmp_gt_f32_e64 s[4:5], s91, v131
	v_cndmask_b32_e32 v138, v138, v139, vcc
	v_rsq_f32_e32 v138, v138
	v_cndmask_b32_e64 v131, v131, v132, s[4:5]
	v_rsq_f32_e32 v131, v131
	s_nop 0
	v_mul_f32_e32 v139, 0x45800000, v138
	v_cndmask_b32_e32 v138, v138, v139, vcc
	v_mul_f32_e32 v132, 0x45800000, v131
	v_cmp_gt_f32_e32 vcc, s91, v130
	v_cndmask_b32_e64 v132, v131, v132, s[4:5]
	v_mul_f32_e32 v131, 0x4b800000, v130
	v_cndmask_b32_e32 v130, v130, v131, vcc
	v_rsq_f32_e32 v130, v130
	s_nop 0
	s_nop 0
	s_nop 0
	v_mul_f32_e32 v131, 0x45800000, v130
	v_cndmask_b32_e32 v130, v130, v131, vcc
	v_mov_b32_e32 v236, v194
	v_mov_b32_e32 v237, v192
	v_mov_b32_e32 v238, v148
	v_mov_b32_e32 v239, v146
	v_mov_b32_e32 v248, v140
	v_mov_b32_e32 v249, v138
	v_mov_b32_e32 v250, v132
	v_mov_b32_e32 v251, v130
	s_mov_b32 s101, s36
	s_branch .Lgu_rs_done
.Lgu_rs_cached:
	v_lshl_add_u32 v188, s36, 8, v193
	v_lshl_or_b32 v190, s35, 7, v198
	s_movk_i32 s9, 0x1600
	v_or_b32_e32 v186, 16, v188
	v_or_b32_e32 v184, 32, v188
	v_or_b32_e32 v182, 48, v188
	v_add_u32_e32 v180, 0x80, v188
	v_add_u32_e32 v178, 0x90, v188
	v_add_u32_e32 v176, 0xa0, v188
	v_add_u32_e32 v174, 0xb0, v188
	v_ashrrev_i32_e32 v191, 31, v190
	v_mov_b32_e32 v194, v236
	v_mov_b32_e32 v192, v237
	v_mov_b32_e32 v148, v238
	v_mov_b32_e32 v146, v239
	v_mov_b32_e32 v140, v248
	v_mov_b32_e32 v138, v249
	v_mov_b32_e32 v132, v250
	v_mov_b32_e32 v130, v251
.Lgu_rs_done:
	v_readlane_b32 s4, v254, 32
	v_readlane_b32 s5, v254, 33
	v_pk_mul_f32 v[126:127], v[126:127], v[194:195] op_sel_hi:[1,0]
	v_pk_mul_f32 v[122:123], v[122:123], v[194:195] op_sel_hi:[1,0]
	v_pk_mul_f32 v[124:125], v[124:125], v[194:195] op_sel_hi:[1,0]
	v_pk_mul_f32 v[118:119], v[118:119], v[194:195] op_sel_hi:[1,0]
	v_pk_mul_f32 v[114:115], v[114:115], v[194:195] op_sel_hi:[1,0]
	v_pk_mul_f32 v[116:117], v[116:117], v[194:195] op_sel_hi:[1,0]
	v_mul_f32_e32 v131, 0xbfb8aa3b, v126
	v_exp_f32_e32 v131, v131
	v_pk_mul_f32 v[110:111], v[110:111], v[192:193] op_sel_hi:[1,0]
	v_pk_mul_f32 v[106:107], v[106:107], v[192:193] op_sel_hi:[1,0]
	v_pk_mul_f32 v[108:109], v[108:109], v[192:193] op_sel_hi:[1,0]
	v_add_f32_e32 v131, 1.0, v131
	v_rcp_f32_e32 v134, v131
	v_mul_f32_e32 v131, 0xbfb8aa3b, v127
	v_exp_f32_e32 v131, v131
	v_pk_mul_f32 v[102:103], v[102:103], v[192:193] op_sel_hi:[1,0]
	v_pk_mul_f32 v[98:99], v[98:99], v[192:193] op_sel_hi:[1,0]
	v_pk_mul_f32 v[100:101], v[100:101], v[192:193] op_sel_hi:[1,0]
	v_add_f32_e32 v131, 1.0, v131
	v_rcp_f32_e32 v135, v131
	v_pk_mul_f32 v[94:95], v[94:95], v[148:149] op_sel_hi:[1,0]
	v_pk_mul_f32 v[90:91], v[90:91], v[148:149] op_sel_hi:[1,0]
	v_pk_mul_f32 v[92:93], v[92:93], v[148:149] op_sel_hi:[1,0]
	v_pk_mul_f32 v[126:127], v[126:127], v[134:135]
	v_pk_mul_f32 v[86:87], v[86:87], v[148:149] op_sel_hi:[1,0]
	v_pk_mul_f32 v[122:123], v[122:123], v[126:127]
	v_pk_mul_f32 v[126:127], v[128:129], v[194:195] op_sel_hi:[1,0]
	v_pk_mul_f32 v[82:83], v[82:83], v[148:149] op_sel_hi:[1,0]
	v_mul_f32_e32 v128, 0xbfb8aa3b, v126
	v_mul_f32_e32 v129, 0xbfb8aa3b, v127
	v_exp_f32_e32 v128, v128
	v_exp_f32_e32 v129, v129
	v_pk_mul_f32 v[84:85], v[84:85], v[148:149] op_sel_hi:[1,0]
	v_pk_mul_f32 v[78:79], v[78:79], v[146:147] op_sel_hi:[1,0]
	v_add_f32_e32 v128, 1.0, v128
	v_add_f32_e32 v129, 1.0, v129
	v_rcp_f32_e32 v128, v128
	v_rcp_f32_e32 v129, v129
	v_pk_mul_f32 v[74:75], v[74:75], v[146:147] op_sel_hi:[1,0]
	v_pk_mul_f32 v[76:77], v[76:77], v[146:147] op_sel_hi:[1,0]
	v_pk_mul_f32 v[70:71], v[70:71], v[146:147] op_sel_hi:[1,0]
	v_pk_mul_f32 v[126:127], v[126:127], v[128:129]
	v_pk_mul_f32 v[66:67], v[66:67], v[146:147] op_sel_hi:[1,0]
	v_pk_mul_f32 v[124:125], v[124:125], v[126:127]
	v_mul_f32_e32 v126, 0xbfb8aa3b, v118
	v_mul_f32_e32 v127, 0xbfb8aa3b, v119
	v_exp_f32_e32 v126, v126
	v_exp_f32_e32 v127, v127
	v_pk_mul_f32 v[68:69], v[68:69], v[146:147] op_sel_hi:[1,0]
	v_pk_mul_f32 v[62:63], v[62:63], v[140:141] op_sel_hi:[1,0]
	v_add_f32_e32 v126, 1.0, v126
	v_add_f32_e32 v127, 1.0, v127
	v_rcp_f32_e32 v126, v126
	v_rcp_f32_e32 v127, v127
	v_pk_mul_f32 v[58:59], v[58:59], v[140:141] op_sel_hi:[1,0]
	v_pk_mul_f32 v[60:61], v[60:61], v[140:141] op_sel_hi:[1,0]
	v_pk_mul_f32 v[54:55], v[54:55], v[140:141] op_sel_hi:[1,0]
	v_pk_mul_f32 v[118:119], v[118:119], v[126:127]
	v_pk_mul_f32 v[50:51], v[50:51], v[140:141] op_sel_hi:[1,0]
	v_pk_mul_f32 v[114:115], v[114:115], v[118:119]
	v_pk_mul_f32 v[118:119], v[120:121], v[194:195] op_sel_hi:[1,0]
	v_pk_mul_f32 v[52:53], v[52:53], v[140:141] op_sel_hi:[1,0]
	v_mul_f32_e32 v120, 0xbfb8aa3b, v118
	v_mul_f32_e32 v121, 0xbfb8aa3b, v119
	v_exp_f32_e32 v120, v120
	v_exp_f32_e32 v121, v121
	v_pk_mul_f32 v[46:47], v[46:47], v[138:139] op_sel_hi:[1,0]
	v_pk_mul_f32 v[42:43], v[42:43], v[138:139] op_sel_hi:[1,0]
	v_add_f32_e32 v120, 1.0, v120
	v_add_f32_e32 v121, 1.0, v121
	v_rcp_f32_e32 v120, v120
	v_rcp_f32_e32 v121, v121
	v_pk_mul_f32 v[44:45], v[44:45], v[138:139] op_sel_hi:[1,0]
	v_pk_mul_f32 v[38:39], v[38:39], v[138:139] op_sel_hi:[1,0]
	v_pk_mul_f32 v[34:35], v[34:35], v[138:139] op_sel_hi:[1,0]
	v_pk_mul_f32 v[118:119], v[118:119], v[120:121]
	v_cvt_pk_bf16_f32 v120, v114, v115
	v_pk_mul_f32 v[116:117], v[116:117], v[118:119]
	v_mov_b64_e32 v[114:115], s[4:5]
	v_cvt_pk_bf16_f32 v118, v122, v123
	v_cvt_pk_bf16_f32 v121, v116, v117
	v_mad_i64_i32 v[122:123], s[4:5], v188, s9, v[114:115]
	v_lshlrev_b64 v[116:117], 1, v[190:191]
	v_cvt_pk_bf16_f32 v119, v124, v125
	v_lshl_add_u64 v[122:123], v[122:123], 0, v[116:117]
	global_store_dwordx4 v[122:123], v[118:121], off
	v_pk_mul_f32 v[36:37], v[36:37], v[138:139] op_sel_hi:[1,0]
	v_pk_mul_f32 v[30:31], v[30:31], v[132:133] op_sel_hi:[1,0]
	v_mul_f32_e32 v118, 0xbfb8aa3b, v110
	v_mul_f32_e32 v119, 0xbfb8aa3b, v111
	v_exp_f32_e32 v118, v118
	v_exp_f32_e32 v119, v119
	v_pk_mul_f32 v[26:27], v[26:27], v[132:133] op_sel_hi:[1,0]
	v_pk_mul_f32 v[28:29], v[28:29], v[132:133] op_sel_hi:[1,0]
	v_add_f32_e32 v118, 1.0, v118
	v_add_f32_e32 v119, 1.0, v119
	v_rcp_f32_e32 v118, v118
	v_rcp_f32_e32 v119, v119
	v_pk_mul_f32 v[22:23], v[22:23], v[132:133] op_sel_hi:[1,0]
	v_pk_mul_f32 v[18:19], v[18:19], v[132:133] op_sel_hi:[1,0]
	v_pk_mul_f32 v[20:21], v[20:21], v[132:133] op_sel_hi:[1,0]
	v_pk_mul_f32 v[110:111], v[110:111], v[118:119]
	v_pk_mul_f32 v[14:15], v[14:15], v[130:131] op_sel_hi:[1,0]
	v_pk_mul_f32 v[106:107], v[106:107], v[110:111]
	v_pk_mul_f32 v[110:111], v[112:113], v[192:193] op_sel_hi:[1,0]
	v_pk_mul_f32 v[10:11], v[10:11], v[130:131] op_sel_hi:[1,0]
	v_mul_f32_e32 v112, 0xbfb8aa3b, v110
	v_mul_f32_e32 v113, 0xbfb8aa3b, v111
	v_exp_f32_e32 v112, v112
	v_exp_f32_e32 v113, v113
	v_pk_mul_f32 v[12:13], v[12:13], v[130:131] op_sel_hi:[1,0]
	v_pk_mul_f32 v[6:7], v[6:7], v[130:131] op_sel_hi:[1,0]
	v_add_f32_e32 v112, 1.0, v112
	v_add_f32_e32 v113, 1.0, v113
	v_rcp_f32_e32 v112, v112
	v_rcp_f32_e32 v113, v113
	v_pk_mul_f32 v[2:3], v[2:3], v[130:131] op_sel_hi:[1,0]
	v_pk_mul_f32 v[4:5], v[4:5], v[130:131] op_sel_hi:[1,0]
	s_andn2_b64 vcc, exec, s[0:1]
	v_pk_mul_f32 v[110:111], v[110:111], v[112:113]
	s_nop 0
	v_pk_mul_f32 v[108:109], v[108:109], v[110:111]
	v_mul_f32_e32 v110, 0xbfb8aa3b, v102
	v_mul_f32_e32 v111, 0xbfb8aa3b, v103
	v_exp_f32_e32 v110, v110
	v_exp_f32_e32 v111, v111
	v_add_f32_e32 v110, 1.0, v110
	v_add_f32_e32 v111, 1.0, v111
	v_rcp_f32_e32 v110, v110
	v_rcp_f32_e32 v111, v111
	s_nop 0
	v_pk_mul_f32 v[102:103], v[102:103], v[110:111]
	s_nop 0
	v_pk_mul_f32 v[102:103], v[98:99], v[102:103]
	v_pk_mul_f32 v[98:99], v[104:105], v[192:193] op_sel_hi:[1,0]
	s_nop 0
	v_mul_f32_e32 v104, 0xbfb8aa3b, v98
	v_mul_f32_e32 v105, 0xbfb8aa3b, v99
	v_exp_f32_e32 v104, v104
	v_exp_f32_e32 v105, v105
	v_add_f32_e32 v104, 1.0, v104
	v_add_f32_e32 v105, 1.0, v105
	v_rcp_f32_e32 v104, v104
	v_rcp_f32_e32 v105, v105
	s_nop 0
	v_pk_mul_f32 v[98:99], v[98:99], v[104:105]
	s_nop 0
	v_pk_mul_f32 v[104:105], v[100:101], v[98:99]
	v_cvt_pk_bf16_f32 v100, v102, v103
	v_mad_i64_i32 v[102:103], s[4:5], v186, s9, v[114:115]
	v_cvt_pk_bf16_f32 v98, v106, v107
	v_cvt_pk_bf16_f32 v99, v108, v109
	v_cvt_pk_bf16_f32 v101, v104, v105
	v_lshl_add_u64 v[102:103], v[102:103], 0, v[116:117]
	global_store_dwordx4 v[102:103], v[98:101], off
	s_nop 1
	v_mul_f32_e32 v98, 0xbfb8aa3b, v94
	v_mul_f32_e32 v99, 0xbfb8aa3b, v95
	v_exp_f32_e32 v98, v98
	v_exp_f32_e32 v99, v99
	v_add_f32_e32 v98, 1.0, v98
	v_add_f32_e32 v99, 1.0, v99
	v_rcp_f32_e32 v98, v98
	v_rcp_f32_e32 v99, v99
	s_nop 0
	v_pk_mul_f32 v[94:95], v[94:95], v[98:99]
	s_nop 0
	v_pk_mul_f32 v[90:91], v[90:91], v[94:95]
	v_pk_mul_f32 v[94:95], v[96:97], v[148:149] op_sel_hi:[1,0]
	s_nop 0
	v_mul_f32_e32 v96, 0xbfb8aa3b, v94
	v_mul_f32_e32 v97, 0xbfb8aa3b, v95
	v_exp_f32_e32 v96, v96
	v_exp_f32_e32 v97, v97
	v_add_f32_e32 v96, 1.0, v96
	v_add_f32_e32 v97, 1.0, v97
	v_rcp_f32_e32 v96, v96
	v_rcp_f32_e32 v97, v97
	s_nop 0
	v_pk_mul_f32 v[94:95], v[94:95], v[96:97]
	s_nop 0
	v_pk_mul_f32 v[92:93], v[92:93], v[94:95]
	v_mul_f32_e32 v94, 0xbfb8aa3b, v86
	v_mul_f32_e32 v95, 0xbfb8aa3b, v87
	v_exp_f32_e32 v94, v94
	v_exp_f32_e32 v95, v95
	v_add_f32_e32 v94, 1.0, v94
	v_add_f32_e32 v95, 1.0, v95
	v_rcp_f32_e32 v94, v94
	v_rcp_f32_e32 v95, v95
	s_nop 0
	v_pk_mul_f32 v[86:87], v[86:87], v[94:95]
	s_nop 0
	v_pk_mul_f32 v[86:87], v[82:83], v[86:87]
	v_pk_mul_f32 v[82:83], v[88:89], v[148:149] op_sel_hi:[1,0]
	s_nop 0
	v_mul_f32_e32 v88, 0xbfb8aa3b, v82
	v_mul_f32_e32 v89, 0xbfb8aa3b, v83
	v_exp_f32_e32 v88, v88
	v_exp_f32_e32 v89, v89
	v_add_f32_e32 v88, 1.0, v88
	v_add_f32_e32 v89, 1.0, v89
	v_rcp_f32_e32 v88, v88
	v_rcp_f32_e32 v89, v89
	s_nop 0
	v_pk_mul_f32 v[82:83], v[82:83], v[88:89]
	s_nop 0
	v_pk_mul_f32 v[88:89], v[84:85], v[82:83]
	v_cvt_pk_bf16_f32 v84, v86, v87
	v_mad_i64_i32 v[86:87], s[4:5], v184, s9, v[114:115]
	v_cvt_pk_bf16_f32 v82, v90, v91
	v_cvt_pk_bf16_f32 v83, v92, v93
	v_cvt_pk_bf16_f32 v85, v88, v89
	v_lshl_add_u64 v[86:87], v[86:87], 0, v[116:117]
	global_store_dwordx4 v[86:87], v[82:85], off
	s_nop 1
	v_mul_f32_e32 v82, 0xbfb8aa3b, v78
	v_mul_f32_e32 v83, 0xbfb8aa3b, v79
	v_exp_f32_e32 v82, v82
	v_exp_f32_e32 v83, v83
	v_add_f32_e32 v82, 1.0, v82
	v_add_f32_e32 v83, 1.0, v83
	v_rcp_f32_e32 v82, v82
	v_rcp_f32_e32 v83, v83
	s_nop 0
	v_pk_mul_f32 v[78:79], v[78:79], v[82:83]
	s_nop 0
	v_pk_mul_f32 v[74:75], v[74:75], v[78:79]
	v_pk_mul_f32 v[78:79], v[80:81], v[146:147] op_sel_hi:[1,0]
	s_nop 0
	v_mul_f32_e32 v80, 0xbfb8aa3b, v78
	v_mul_f32_e32 v81, 0xbfb8aa3b, v79
	v_exp_f32_e32 v80, v80
	v_exp_f32_e32 v81, v81
	v_add_f32_e32 v80, 1.0, v80
	v_add_f32_e32 v81, 1.0, v81
	v_rcp_f32_e32 v80, v80
	v_rcp_f32_e32 v81, v81
	s_nop 0
	v_pk_mul_f32 v[78:79], v[78:79], v[80:81]
	s_nop 0
	v_pk_mul_f32 v[76:77], v[76:77], v[78:79]
	v_mul_f32_e32 v78, 0xbfb8aa3b, v70
	v_mul_f32_e32 v79, 0xbfb8aa3b, v71
	v_exp_f32_e32 v78, v78
	v_exp_f32_e32 v79, v79
	v_add_f32_e32 v78, 1.0, v78
	v_add_f32_e32 v79, 1.0, v79
	v_rcp_f32_e32 v78, v78
	v_rcp_f32_e32 v79, v79
	s_nop 0
	v_pk_mul_f32 v[70:71], v[70:71], v[78:79]
	s_nop 0
	v_pk_mul_f32 v[70:71], v[66:67], v[70:71]
	v_pk_mul_f32 v[66:67], v[72:73], v[146:147] op_sel_hi:[1,0]
	s_nop 0
	v_mul_f32_e32 v72, 0xbfb8aa3b, v66
	v_mul_f32_e32 v73, 0xbfb8aa3b, v67
	v_exp_f32_e32 v72, v72
	v_exp_f32_e32 v73, v73
	v_add_f32_e32 v72, 1.0, v72
	v_add_f32_e32 v73, 1.0, v73
	v_rcp_f32_e32 v72, v72
	v_rcp_f32_e32 v73, v73
	s_nop 0
	v_pk_mul_f32 v[66:67], v[66:67], v[72:73]
	s_nop 0
	v_pk_mul_f32 v[72:73], v[68:69], v[66:67]
	v_cvt_pk_bf16_f32 v68, v70, v71
	v_mad_i64_i32 v[70:71], s[4:5], v182, s9, v[114:115]
	v_cvt_pk_bf16_f32 v66, v74, v75
	v_cvt_pk_bf16_f32 v67, v76, v77
	v_cvt_pk_bf16_f32 v69, v72, v73
	v_lshl_add_u64 v[70:71], v[70:71], 0, v[116:117]
	global_store_dwordx4 v[70:71], v[66:69], off
	s_nop 1
	v_mul_f32_e32 v66, 0xbfb8aa3b, v62
	v_mul_f32_e32 v67, 0xbfb8aa3b, v63
	v_exp_f32_e32 v66, v66
	v_exp_f32_e32 v67, v67
	v_add_f32_e32 v66, 1.0, v66
	v_add_f32_e32 v67, 1.0, v67
	v_rcp_f32_e32 v66, v66
	v_rcp_f32_e32 v67, v67
	s_nop 0
	v_pk_mul_f32 v[62:63], v[62:63], v[66:67]
	s_nop 0
	v_pk_mul_f32 v[58:59], v[58:59], v[62:63]
	v_pk_mul_f32 v[62:63], v[64:65], v[140:141] op_sel_hi:[1,0]
	s_nop 0
	v_mul_f32_e32 v64, 0xbfb8aa3b, v62
	v_mul_f32_e32 v65, 0xbfb8aa3b, v63
	v_exp_f32_e32 v64, v64
	v_exp_f32_e32 v65, v65
	v_add_f32_e32 v64, 1.0, v64
	v_add_f32_e32 v65, 1.0, v65
	v_rcp_f32_e32 v64, v64
	v_rcp_f32_e32 v65, v65
	s_nop 0
	v_pk_mul_f32 v[62:63], v[62:63], v[64:65]
	s_nop 0
	v_pk_mul_f32 v[60:61], v[60:61], v[62:63]
	v_mul_f32_e32 v62, 0xbfb8aa3b, v54
	v_mul_f32_e32 v63, 0xbfb8aa3b, v55
	v_exp_f32_e32 v62, v62
	v_exp_f32_e32 v63, v63
	v_add_f32_e32 v62, 1.0, v62
	v_add_f32_e32 v63, 1.0, v63
	v_rcp_f32_e32 v62, v62
	v_rcp_f32_e32 v63, v63
	s_nop 0
	v_pk_mul_f32 v[54:55], v[54:55], v[62:63]
	s_nop 0
	v_pk_mul_f32 v[54:55], v[50:51], v[54:55]
	v_pk_mul_f32 v[50:51], v[56:57], v[140:141] op_sel_hi:[1,0]
	s_nop 0
	v_mul_f32_e32 v56, 0xbfb8aa3b, v50
	v_mul_f32_e32 v57, 0xbfb8aa3b, v51
	v_exp_f32_e32 v56, v56
	v_exp_f32_e32 v57, v57
	v_add_f32_e32 v56, 1.0, v56
	v_add_f32_e32 v57, 1.0, v57
	v_rcp_f32_e32 v56, v56
	v_rcp_f32_e32 v57, v57
	s_nop 0
	v_pk_mul_f32 v[50:51], v[50:51], v[56:57]
	s_nop 0
	v_pk_mul_f32 v[56:57], v[52:53], v[50:51]
	v_cvt_pk_bf16_f32 v52, v54, v55
	v_mad_i64_i32 v[54:55], s[4:5], v180, s9, v[114:115]
	v_cvt_pk_bf16_f32 v50, v58, v59
	v_cvt_pk_bf16_f32 v51, v60, v61
	v_cvt_pk_bf16_f32 v53, v56, v57
	v_lshl_add_u64 v[54:55], v[54:55], 0, v[116:117]
	global_store_dwordx4 v[54:55], v[50:53], off
	s_nop 1
	v_mul_f32_e32 v50, 0xbfb8aa3b, v46
	v_mul_f32_e32 v51, 0xbfb8aa3b, v47
	v_exp_f32_e32 v50, v50
	v_exp_f32_e32 v51, v51
	v_add_f32_e32 v50, 1.0, v50
	v_add_f32_e32 v51, 1.0, v51
	v_rcp_f32_e32 v50, v50
	v_rcp_f32_e32 v51, v51
	s_nop 0
	v_pk_mul_f32 v[46:47], v[46:47], v[50:51]
	s_nop 0
	v_pk_mul_f32 v[42:43], v[42:43], v[46:47]
	v_pk_mul_f32 v[46:47], v[48:49], v[138:139] op_sel_hi:[1,0]
	s_nop 0
	v_mul_f32_e32 v48, 0xbfb8aa3b, v46
	v_mul_f32_e32 v49, 0xbfb8aa3b, v47
	v_exp_f32_e32 v48, v48
	v_exp_f32_e32 v49, v49
	v_add_f32_e32 v48, 1.0, v48
	v_add_f32_e32 v49, 1.0, v49
	v_rcp_f32_e32 v48, v48
	v_rcp_f32_e32 v49, v49
	s_nop 0
	v_pk_mul_f32 v[46:47], v[46:47], v[48:49]
	s_nop 0
	v_pk_mul_f32 v[44:45], v[44:45], v[46:47]
	v_mul_f32_e32 v46, 0xbfb8aa3b, v38
	v_mul_f32_e32 v47, 0xbfb8aa3b, v39
	v_exp_f32_e32 v46, v46
	v_exp_f32_e32 v47, v47
	v_add_f32_e32 v46, 1.0, v46
	v_add_f32_e32 v47, 1.0, v47
	v_rcp_f32_e32 v46, v46
	v_rcp_f32_e32 v47, v47
	s_nop 0
	v_pk_mul_f32 v[38:39], v[38:39], v[46:47]
	s_nop 0
	v_pk_mul_f32 v[38:39], v[34:35], v[38:39]
	v_pk_mul_f32 v[34:35], v[40:41], v[138:139] op_sel_hi:[1,0]
	s_nop 0
	v_mul_f32_e32 v40, 0xbfb8aa3b, v34
	v_mul_f32_e32 v41, 0xbfb8aa3b, v35
	v_exp_f32_e32 v40, v40
	v_exp_f32_e32 v41, v41
	v_add_f32_e32 v40, 1.0, v40
	v_add_f32_e32 v41, 1.0, v41
	v_rcp_f32_e32 v40, v40
	v_rcp_f32_e32 v41, v41
	s_nop 0
	v_pk_mul_f32 v[34:35], v[34:35], v[40:41]
	s_nop 0
	v_pk_mul_f32 v[40:41], v[36:37], v[34:35]
	v_cvt_pk_bf16_f32 v36, v38, v39
	v_mad_i64_i32 v[38:39], s[4:5], v178, s9, v[114:115]
	v_cvt_pk_bf16_f32 v34, v42, v43
	v_cvt_pk_bf16_f32 v35, v44, v45
	v_cvt_pk_bf16_f32 v37, v40, v41
	v_lshl_add_u64 v[38:39], v[38:39], 0, v[116:117]
	global_store_dwordx4 v[38:39], v[34:37], off
	s_nop 1
	v_mul_f32_e32 v34, 0xbfb8aa3b, v30
	v_mul_f32_e32 v35, 0xbfb8aa3b, v31
	v_exp_f32_e32 v34, v34
	v_exp_f32_e32 v35, v35
	v_add_f32_e32 v34, 1.0, v34
	v_add_f32_e32 v35, 1.0, v35
	v_rcp_f32_e32 v34, v34
	v_rcp_f32_e32 v35, v35
	s_nop 0
	v_pk_mul_f32 v[30:31], v[30:31], v[34:35]
	s_nop 0
	v_pk_mul_f32 v[26:27], v[26:27], v[30:31]
	v_pk_mul_f32 v[30:31], v[32:33], v[132:133] op_sel_hi:[1,0]
	s_nop 0
	v_mul_f32_e32 v32, 0xbfb8aa3b, v30
	v_mul_f32_e32 v33, 0xbfb8aa3b, v31
	v_exp_f32_e32 v32, v32
	v_exp_f32_e32 v33, v33
	v_add_f32_e32 v32, 1.0, v32
	v_add_f32_e32 v33, 1.0, v33
	v_rcp_f32_e32 v32, v32
	v_rcp_f32_e32 v33, v33
	s_nop 0
	v_pk_mul_f32 v[30:31], v[30:31], v[32:33]
	s_nop 0
	v_pk_mul_f32 v[28:29], v[28:29], v[30:31]
	v_mul_f32_e32 v30, 0xbfb8aa3b, v22
	v_mul_f32_e32 v31, 0xbfb8aa3b, v23
	v_exp_f32_e32 v30, v30
	v_exp_f32_e32 v31, v31
	v_add_f32_e32 v30, 1.0, v30
	v_add_f32_e32 v31, 1.0, v31
	v_rcp_f32_e32 v30, v30
	v_rcp_f32_e32 v31, v31
	s_nop 0
	v_pk_mul_f32 v[22:23], v[22:23], v[30:31]
	s_nop 0
	v_pk_mul_f32 v[22:23], v[18:19], v[22:23]
	v_pk_mul_f32 v[18:19], v[24:25], v[132:133] op_sel_hi:[1,0]
	s_nop 0
	v_mul_f32_e32 v24, 0xbfb8aa3b, v18
	v_mul_f32_e32 v25, 0xbfb8aa3b, v19
	v_exp_f32_e32 v24, v24
	v_exp_f32_e32 v25, v25
	v_add_f32_e32 v24, 1.0, v24
	v_add_f32_e32 v25, 1.0, v25
	v_rcp_f32_e32 v24, v24
	v_rcp_f32_e32 v25, v25
	s_nop 0
	v_pk_mul_f32 v[18:19], v[18:19], v[24:25]
	s_nop 0
	v_pk_mul_f32 v[24:25], v[20:21], v[18:19]
	v_cvt_pk_bf16_f32 v20, v22, v23
	v_mad_i64_i32 v[22:23], s[4:5], v176, s9, v[114:115]
	v_cvt_pk_bf16_f32 v18, v26, v27
	v_cvt_pk_bf16_f32 v19, v28, v29
	v_cvt_pk_bf16_f32 v21, v24, v25
	v_lshl_add_u64 v[22:23], v[22:23], 0, v[116:117]
	global_store_dwordx4 v[22:23], v[18:21], off
	s_nop 1
	v_mul_f32_e32 v18, 0xbfb8aa3b, v14
	v_mul_f32_e32 v19, 0xbfb8aa3b, v15
	v_exp_f32_e32 v18, v18
	v_exp_f32_e32 v19, v19
	v_add_f32_e32 v18, 1.0, v18
	v_add_f32_e32 v19, 1.0, v19
	v_rcp_f32_e32 v18, v18
	v_rcp_f32_e32 v19, v19
	s_nop 0
	v_pk_mul_f32 v[14:15], v[14:15], v[18:19]
	s_nop 0
	v_pk_mul_f32 v[10:11], v[10:11], v[14:15]
	v_pk_mul_f32 v[14:15], v[16:17], v[130:131] op_sel_hi:[1,0]
	s_nop 0
	v_mul_f32_e32 v16, 0xbfb8aa3b, v14
	v_mul_f32_e32 v17, 0xbfb8aa3b, v15
	v_exp_f32_e32 v16, v16
	v_exp_f32_e32 v17, v17
	v_add_f32_e32 v16, 1.0, v16
	v_add_f32_e32 v17, 1.0, v17
	v_rcp_f32_e32 v16, v16
	v_rcp_f32_e32 v17, v17
	s_nop 0
	v_pk_mul_f32 v[14:15], v[14:15], v[16:17]
	s_nop 0
	v_pk_mul_f32 v[12:13], v[12:13], v[14:15]
	v_mul_f32_e32 v14, 0xbfb8aa3b, v6
	v_mul_f32_e32 v15, 0xbfb8aa3b, v7
	v_exp_f32_e32 v14, v14
	v_exp_f32_e32 v15, v15
	v_add_f32_e32 v14, 1.0, v14
	v_add_f32_e32 v15, 1.0, v15
	v_rcp_f32_e32 v14, v14
	v_rcp_f32_e32 v15, v15
	s_nop 0
	v_pk_mul_f32 v[6:7], v[6:7], v[14:15]
	s_nop 0
	v_pk_mul_f32 v[6:7], v[2:3], v[6:7]
	v_pk_mul_f32 v[2:3], v[8:9], v[130:131] op_sel_hi:[1,0]
	s_nop 0
	v_mul_f32_e32 v8, 0xbfb8aa3b, v2
	v_mul_f32_e32 v9, 0xbfb8aa3b, v3
	v_exp_f32_e32 v8, v8
	v_exp_f32_e32 v9, v9
	v_add_f32_e32 v8, 1.0, v8
	v_add_f32_e32 v9, 1.0, v9
	v_rcp_f32_e32 v8, v8
	v_rcp_f32_e32 v9, v9
	s_nop 0
	v_pk_mul_f32 v[2:3], v[2:3], v[8:9]
	s_nop 0
	v_pk_mul_f32 v[8:9], v[4:5], v[2:3]
	v_cvt_pk_bf16_f32 v4, v6, v7
	v_mad_i64_i32 v[6:7], s[4:5], v174, s9, v[114:115]
	v_cvt_pk_bf16_f32 v2, v10, v11
	v_cvt_pk_bf16_f32 v3, v12, v13
	v_cvt_pk_bf16_f32 v5, v8, v9
	v_lshl_add_u64 v[6:7], v[6:7], 0, v[116:117]
	s_mov_b64 s[4:5], -1
	global_store_dwordx4 v[6:7], v[2:5], off
	s_cbranch_vccnz .LBB0_1438
	s_andn2_b64 vcc, exec, s[2:3]
	s_cbranch_vccnz .LBB0_1437
	s_barrier
	s_branch .LBB0_1437

	.amdhsa_kernel _Z3fwd4Args
		.amdhsa_group_segment_fixed_size 0
		.amdhsa_private_segment_fixed_size 0
		.amdhsa_kernarg_size 552
		.amdhsa_user_sgpr_count 2
		.amdhsa_user_sgpr_dispatch_ptr 0
		.amdhsa_user_sgpr_queue_ptr 0
		.amdhsa_user_sgpr_kernarg_segment_ptr 1
		.amdhsa_user_sgpr_dispatch_id 0
		.amdhsa_user_sgpr_kernarg_preload_length 0
		.amdhsa_user_sgpr_kernarg_preload_offset 0
		.amdhsa_user_sgpr_private_segment_size 0
		.amdhsa_uses_dynamic_stack 0
		.amdhsa_enable_private_segment 0
		.amdhsa_system_sgpr_workgroup_id_x 1
		.amdhsa_system_sgpr_workgroup_id_y 0
		.amdhsa_system_sgpr_workgroup_id_z 0
		.amdhsa_system_sgpr_workgroup_info 0
		.amdhsa_system_vgpr_workitem_id 2
		.amdhsa_next_free_vgpr 256
		.amdhsa_next_free_sgpr 102
		.amdhsa_accum_offset 256
		.amdhsa_reserve_vcc 1
		.amdhsa_float_round_mode_32 0
		.amdhsa_float_round_mode_16_64 0
		.amdhsa_float_denorm_mode_32 3
		.amdhsa_float_denorm_mode_16_64 3
		.amdhsa_dx10_clamp 1
		.amdhsa_ieee_mode 1
		.amdhsa_fp16_overflow 0
		.amdhsa_tg_split 0
		.amdhsa_exception_fp_ieee_invalid_op 0
		.amdhsa_exception_fp_denorm_src 0
		.amdhsa_exception_fp_ieee_div_zero 0
		.amdhsa_exception_fp_ieee_overflow 0
		.amdhsa_exception_fp_ieee_underflow 0
		.amdhsa_exception_fp_ieee_inexact 0
		.amdhsa_exception_int_div_zero 0
	.end_amdhsa_kernel

amdhsa.kernels:
  - .agpr_count:     0
    .args:
      - .offset:         0
        .size:           296
        .value_kind:     by_value
      - .offset:         296
        .size:           4
        .value_kind:     hidden_block_count_x
      - .offset:         300
        .size:           4
        .value_kind:     hidden_block_count_y
      - .offset:         304
        .size:           4
        .value_kind:     hidden_block_count_z
      - .offset:         308
        .size:           2
        .value_kind:     hidden_group_size_x
      - .offset:         310
        .size:           2
        .value_kind:     hidden_group_size_y
      - .offset:         312
        .size:           2
        .value_kind:     hidden_group_size_z
      - .offset:         314
        .size:           2
        .value_kind:     hidden_remainder_x
      - .offset:         316
        .size:           2
        .value_kind:     hidden_remainder_y
      - .offset:         318
        .size:           2
        .value_kind:     hidden_remainder_z
      - .offset:         336
        .size:           8
        .value_kind:     hidden_global_offset_x
      - .offset:         344
        .size:           8
        .value_kind:     hidden_global_offset_y
      - .offset:         352
        .size:           8
        .value_kind:     hidden_global_offset_z
      - .offset:         360
        .size:           2
        .value_kind:     hidden_grid_dims
      - .offset:         384
        .size:           8
        .value_kind:     hidden_multigrid_sync_arg
      - .offset:         416
        .size:           4
        .value_kind:     hidden_dynamic_lds_size
    .group_segment_fixed_size: 0
    .kernarg_segment_align: 8
    .kernarg_segment_size: 552
    .language:       OpenCL C
    .language_version:
      - 2
      - 0
    .max_flat_workgroup_size: 512
    .name:           _Z3fwd4Args
    .private_segment_fixed_size: 0
    .sgpr_count:     108
    .sgpr_spill_count: 333
    .symbol:         _Z3fwd4Args.kd
    .uniform_work_group_size: 1
    .uses_dynamic_stack: false
    .vgpr_count:     256
    .vgpr_spill_count: 0
    .wavefront_size: 64
